# P5 hgrn_issue(ib): ws pointer via s_load, ib loads issued ahead of ia's progressively-waited unpacking (counts +32)
# speedup vs baseline: 1.0064x; 1.0046x over previous
.LBB0_1140:
	s_mov_b64 s[6:7], s[62:63]
	s_load_dwordx2 s[10:11], s[6:7], 0xc0
	v_mov_b32_e32 v2, v208
	v_readlane_b32 s0, v253, 19
	v_lshlrev_b32_e32 v4, 1, v2
	v_ashrrev_i32_e32 v2, 3, v2
	v_and_b32_e32 v2, -8, v2
	v_add_u32_e32 v2, s0, v2
	v_and_b32_e32 v4, 0x7e, v4
	v_readlane_b32 s0, v253, 20
	v_ashrrev_i32_e32 v12, 31, v2
	v_readlane_b32 s2, v254, 8
	v_or_b32_e32 v166, s40, v4
	v_or_b32_e32 v14, s0, v4
	v_lshlrev_b32_e32 v4, 9, v2
	v_alignbit_b32 v10, v12, v2, 8
	v_readlane_b32 s3, v254, 9
	v_and_b32_e32 v2, 0x1f000, v4
	v_mov_b32_e32 v3, v167
	v_mad_u64_u32 v[4:5], s[8:9], v10, 49, s[2:3]
	v_readlane_b32 s2, v254, 24
	v_readlane_b32 s3, v254, 25
	v_mad_u32_u24 v5, v12, 49, v5
	v_lshlrev_b64 v[4:5], 17, v[4:5]
	v_mad_u64_u32 v[6:7], s[8:9], v10, 49, s[2:3]
	v_readlane_b32 s2, v254, 26
	v_readlane_b32 s3, v254, 27
	v_mad_u32_u24 v7, v12, 49, v7
	v_lshlrev_b64 v[6:7], 17, v[6:7]
	v_mad_u64_u32 v[8:9], s[8:9], v10, 49, s[2:3]
	v_readlane_b32 s2, v254, 10
	v_readlane_b32 s3, v254, 11
	v_mad_u32_u24 v9, v12, 49, v9
	v_lshlrev_b64 v[8:9], 17, v[8:9]
	v_mad_u64_u32 v[10:11], s[8:9], v10, 49, s[2:3]
	v_mad_u32_u24 v11, v12, 49, v11
	s_mov_b64 s[2:3], 0x74c2800
	v_lshlrev_b64 v[10:11], 17, v[10:11]
	s_mov_b64 s[6:7], s[62:63]
	v_mov_b32_e32 v43, v208
	s_movk_i32 s0, 0x820
	s_waitcnt lgkmcnt(0)
	v_mov_b32_e32 v0, s10
	v_mov_b32_e32 v1, s11
	v_lshl_add_u64 v[12:13], v[0:1], 0, s[2:3]
	v_lshl_add_u64 v[0:1], v[166:167], 2, v[0:1]
	v_lshlrev_b32_e32 v166, 1, v14
	v_lshl_add_u64 v[4:5], v[12:13], 0, v[4:5]
	v_lshl_add_u64 v[6:7], v[12:13], 0, v[6:7]
	v_lshl_add_u64 v[8:9], v[12:13], 0, v[8:9]
	v_lshl_add_u64 v[10:11], v[12:13], 0, v[10:11]
	v_add_co_u32_e32 v0, vcc, 0x7380000, v0
	v_lshl_add_u64 v[4:5], v[4:5], 0, v[166:167]
	v_lshl_add_u64 v[6:7], v[6:7], 0, v[166:167]
	v_lshl_add_u64 v[8:9], v[8:9], 0, v[166:167]
	v_lshl_add_u64 v[10:11], v[10:11], 0, v[166:167]
	v_addc_co_u32_e32 v1, vcc, 0, v1, vcc
	v_lshl_add_u64 v[4:5], v[4:5], 0, v[2:3]
	v_lshl_add_u64 v[6:7], v[6:7], 0, v[2:3]
	v_lshl_add_u64 v[8:9], v[8:9], 0, v[2:3]
	v_lshl_add_u64 v[2:3], v[10:11], 0, v[2:3]
	global_load_dwordx2 v[18:19], v[0:1], off
	global_load_dword v93, v[4:5], off
	global_load_dword v90, v[4:5], off offset:512
	global_load_dword v89, v[4:5], off offset:1024
	global_load_dword v79, v[4:5], off offset:1536
	global_load_dword v76, v[4:5], off offset:2048
	global_load_dword v68, v[4:5], off offset:2560
	global_load_dword v67, v[4:5], off offset:3072
	global_load_dword v92, v[6:7], off
	global_load_dword v55, v[6:7], off offset:512
	global_load_dword v54, v[6:7], off offset:1024
	global_load_dword v52, v[6:7], off offset:1536
	global_load_dword v50, v[6:7], off offset:2048
	global_load_dword v48, v[6:7], off offset:2560
	global_load_dword v46, v[6:7], off offset:3072
	global_load_dword v25, v[4:5], off offset:3584
	global_load_dword v41, v[8:9], off
	global_load_dword v39, v[8:9], off offset:512
	global_load_dword v38, v[8:9], off offset:1024
	global_load_dword v37, v[8:9], off offset:1536
	global_load_dword v36, v[8:9], off offset:2048
	global_load_dword v35, v[8:9], off offset:2560
	global_load_dword v34, v[8:9], off offset:3072
	global_load_dword v44, v[6:7], off offset:3584
	global_load_dword v91, v[2:3], off
	global_load_dword v86, v[2:3], off offset:512
	global_load_dword v87, v[2:3], off offset:1024
	global_load_dword v74, v[2:3], off offset:1536
	global_load_dword v75, v[2:3], off offset:2048
	global_load_dword v64, v[2:3], off offset:2560
	global_load_dword v65, v[2:3], off offset:3072
	global_load_dword v27, v[8:9], off offset:3584
	global_load_dword v24, v[2:3], off offset:3584
	s_waitcnt vmcnt(60)
	v_lshlrev_b32_e32 v98, 16, v159
	v_and_b32_e32 v97, 0xffff0000, v159
	s_waitcnt vmcnt(56)
	v_lshlrev_b32_e32 v95, 16, v157
	v_and_b32_e32 v94, 0xffff0000, v157
	s_waitcnt vmcnt(52)
	v_lshlrev_b32_e32 v88, 16, v156
	v_and_b32_e32 v84, 0xffff0000, v156
	s_waitcnt vmcnt(48)
	v_lshlrev_b32_e32 v77, 16, v155
	v_and_b32_e32 v71, 0xffff0000, v155
	s_waitcnt vmcnt(44)
	v_lshlrev_b32_e32 v69, 16, v152
	v_and_b32_e32 v66, 0xffff0000, v152
	s_waitcnt vmcnt(40)
	v_lshlrev_b32_e32 v62, 16, v150
	v_and_b32_e32 v61, 0xffff0000, v150
	s_waitcnt vmcnt(36)
	v_lshlrev_b32_e32 v51, 16, v149
	v_and_b32_e32 v49, 0xffff0000, v149
	v_lshlrev_b32_e32 v56, 16, v144
	v_and_b32_e32 v57, 0xffff0000, v144
	s_waitcnt vmcnt(33)
	v_lshlrev_b32_e32 v1, 16, v160
	v_and_b32_e32 v2, 0xffff0000, v160
	v_mul_f32_e32 v0, 0xbfb8aa3b, v1
	v_mul_f32_e32 v3, 0xbfb8aa3b, v2
	v_exp_f32_e32 v0, v0
	v_exp_f32_e32 v3, v3
	v_pk_add_f32 v[4:5], v[72:73], 1.0 op_sel_hi:[1,0] neg_lo:[1,0] neg_hi:[1,0]
	v_mul_f32_e32 v1, 0x3fb8aa3b, v1
	v_add_f32_e32 v0, 1.0, v0
	v_add_f32_e32 v3, 1.0, v3
	v_rcp_f32_e32 v0, v0
	v_rcp_f32_e32 v3, v3
	v_exp_f32_e32 v6, v1
	v_mul_f32_e32 v1, 0x3fb8aa3b, v2
	v_fma_f32 v0, v4, v0, v72
	v_fma_f32 v3, v5, v3, v73
	v_log_f32_e32 v0, v0
	v_exp_f32_e32 v7, v1
	v_log_f32_e32 v1, v3
	global_load_dwordx2 v[20:21], v167, s[6:7] offset:136
	global_load_dwordx2 v[16:17], v167, s[6:7] offset:192
	v_readlane_b32 s2, v254, 45
	v_and_b32_e32 v45, 63, v43
	v_ashrrev_i32_e32 v40, 6, v43
	v_lshl_add_u32 v58, v45, 3, 0
	v_lshlrev_b32_e32 v59, 2, v45
	v_add_u32_e32 v8, s2, v59
	v_lshl_add_u32 v99, v40, 12, v58
	ds_write_b64 v99, v[0:1]
	v_mad_u64_u32 v[0:1], s[6:7], v40, s0, v[8:9]
	ds_write_b32 v0, v158
	v_mul_f32_e32 v0, 0xbfb8aa3b, v98
	v_mul_f32_e32 v1, 0xbfb8aa3b, v97
	v_exp_f32_e32 v0, v0
	v_exp_f32_e32 v1, v1
	v_add_f32_e32 v2, 1.0, v6
	v_add_f32_e32 v3, 1.0, v7
	v_add_f32_e32 v0, 1.0, v0
	v_add_f32_e32 v1, 1.0, v1
	v_rcp_f32_e32 v2, v2
	v_rcp_f32_e32 v3, v3
	v_rcp_f32_e32 v0, v0
	v_rcp_f32_e32 v1, v1
	v_lshlrev_b32_e32 v33, 3, v40
	v_pk_mul_f32 v[6:7], v[4:5], v[2:3]
	v_fma_f32 v0, v4, v0, v72
	v_fma_f32 v1, v5, v1, v73
	v_mul_f32_e32 v3, 0xbfb8aa3b, v95
	v_log_f32_e32 v0, v0
	v_log_f32_e32 v1, v1
	v_exp_f32_e32 v3, v3
	v_or_b32_e32 v32, 1, v33
	v_lshlrev_b32_e32 v2, 9, v32
	v_add_u32_e32 v96, v58, v2
	ds_write_b64 v96, v[0:1]
	v_add_f32_e32 v0, 1.0, v3
	v_rcp_f32_e32 v2, v0
	v_mul_f32_e32 v0, 0xbfb8aa3b, v94
	v_exp_f32_e32 v3, v0
	s_movk_i32 s0, 0x104
	v_mad_u64_u32 v[0:1], s[6:7], v32, s0, v[8:9]
	v_fma_f32 v1, v4, v2, v72
	v_add_f32_e32 v2, 1.0, v3
	v_rcp_f32_e32 v3, v2
	v_or_b32_e32 v31, 2, v33
	v_log_f32_e32 v2, v1
	v_lshlrev_b32_e32 v1, 9, v31
	v_add_u32_e32 v9, v58, v1
	v_fma_f32 v1, v5, v3, v73
	v_log_f32_e32 v3, v1
	v_mul_f32_e32 v1, 0xbfb8aa3b, v88
	v_exp_f32_e32 v1, v1
	v_mul_f32_e32 v8, 0xbfb8aa3b, v84
	v_exp_f32_e32 v8, v8
	ds_write_b64 v9, v[2:3]
	v_add_f32_e32 v1, 1.0, v1
	v_rcp_f32_e32 v1, v1
	v_add_f32_e32 v2, 1.0, v8
	v_rcp_f32_e32 v3, v2
	v_or_b32_e32 v30, 3, v33
	v_fma_f32 v1, v4, v1, v72
	v_log_f32_e32 v2, v1
	v_fma_f32 v1, v5, v3, v73
	v_log_f32_e32 v3, v1
	v_lshlrev_b32_e32 v1, 9, v30
	v_add_u32_e32 v78, v58, v1
	v_mul_f32_e32 v1, 0xbfb8aa3b, v77
	ds_write_b64 v78, v[2:3]
	v_mul_f32_e32 v2, 0xbfb8aa3b, v71
	v_exp_f32_e32 v1, v1
	v_exp_f32_e32 v2, v2
	v_or_b32_e32 v29, 4, v33
	v_mul_f32_e32 v8, 0xbfb8aa3b, v69
	v_add_f32_e32 v1, 1.0, v1
	v_add_f32_e32 v2, 1.0, v2
	v_rcp_f32_e32 v1, v1
	v_rcp_f32_e32 v3, v2
	v_exp_f32_e32 v8, v8
	v_or_b32_e32 v26, 5, v33
	v_fma_f32 v1, v4, v1, v72
	v_fma_f32 v3, v5, v3, v73
	v_log_f32_e32 v2, v1
	v_log_f32_e32 v3, v3
	v_lshlrev_b32_e32 v1, 9, v29
	v_add_u32_e32 v70, v58, v1
	v_add_f32_e32 v1, 1.0, v8
	ds_write_b64 v70, v[2:3]
	v_mul_f32_e32 v2, 0xbfb8aa3b, v66
	v_exp_f32_e32 v2, v2
	v_rcp_f32_e32 v1, v1
	v_or_b32_e32 v28, 6, v33
	ds_write2_b32 v0, v151, v154 offset1:65
	v_add_f32_e32 v2, 1.0, v2
	v_rcp_f32_e32 v3, v2
	v_fma_f32 v1, v4, v1, v72
	v_log_f32_e32 v2, v1
	v_lshlrev_b32_e32 v1, 9, v26
	v_add_u32_e32 v63, v58, v1
	v_fma_f32 v1, v5, v3, v73
	v_mul_f32_e32 v3, 0xbfb8aa3b, v62
	v_exp_f32_e32 v8, v3
	v_mul_f32_e32 v3, 0xbfb8aa3b, v61
	v_exp_f32_e32 v10, v3
	v_log_f32_e32 v3, v1
	v_add_f32_e32 v1, 1.0, v8
	v_rcp_f32_e32 v1, v1
	v_add_f32_e32 v8, 1.0, v10
	v_rcp_f32_e32 v8, v8
	ds_write_b64 v63, v[2:3]
	v_fma_f32 v1, v4, v1, v72
	v_log_f32_e32 v2, v1
	v_fma_f32 v1, v5, v8, v73
	v_log_f32_e32 v3, v1
	v_lshlrev_b32_e32 v1, 9, v28
	v_add_u32_e32 v60, v58, v1
	v_mul_f32_e32 v1, 0xbfb8aa3b, v51
	ds_write_b64 v60, v[2:3]
	v_mul_f32_e32 v2, 0xbfb8aa3b, v49
	v_exp_f32_e32 v1, v1
	v_exp_f32_e32 v2, v2
	v_add_u32_e32 v3, 0x400, v0
	ds_write2_b32 v0, v147, v148 offset0:130 offset1:195
	v_add_f32_e32 v1, 1.0, v1
	v_add_f32_e32 v2, 1.0, v2
	v_rcp_f32_e32 v1, v1
	v_rcp_f32_e32 v8, v2
	ds_write2_b32 v3, v145, v146 offset0:4 offset1:69
	v_or_b32_e32 v23, 7, v33
	v_fma_f32 v1, v4, v1, v72
	v_fmac_f32_e32 v73, v5, v8
	v_log_f32_e32 v2, v1
	v_log_f32_e32 v3, v73
	v_lshlrev_b32_e32 v1, 9, v23
	v_add_u32_e32 v47, v58, v1
	ds_write_b64 v47, v[2:3]
	ds_write_b32 v0, v153 offset:1560
	v_ashrrev_i32_e32 v0, 31, v43
	v_lshrrev_b32_e32 v0, 26, v0
	v_add_u32_e32 v0, v43, v0
	v_ashrrev_i32_e32 v8, 6, v0
	v_mul_u32_u24_e32 v0, 0x41, v45
	v_lshlrev_b32_e32 v2, 5, v8
	v_lshlrev_b32_e32 v3, 2, v0
	v_add3_u32 v0, s2, v2, v3
	s_waitcnt lgkmcnt(0)
	s_barrier
	ds_read2_b32 v[0:1], v0 offset1:1
	s_movk_i32 s0, 0x900
	v_lshlrev_b32_e32 v42, 1, v45
	v_mul_lo_u32 v14, v8, s0
	v_readlane_b32 s3, v254, 46
	v_add_u32_e32 v100, s2, v3
	v_add_u32_e32 v12, v100, v2
	v_add3_u32 v15, s3, v14, v42
	ds_read2_b32 v[2:3], v12 offset0:2 offset1:3
	ds_read2_b32 v[10:11], v12 offset0:4 offset1:5
	ds_read2_b32 v[12:13], v12 offset0:6 offset1:7
	s_waitcnt lgkmcnt(3)
	ds_write_b16 v15, v0
	v_add_u32_e32 v15, s3, v42
	v_add_u32_e32 v14, v15, v14
	ds_write_b16_d16_hi v14, v0 offset:144
	v_lshl_or_b32 v0, v8, 3, 1
	s_movk_i32 s0, 0x120
	v_mul_lo_u32 v0, v0, s0
	v_add3_u32 v8, s3, v0, v42
	v_add_u32_e32 v14, v15, v0
	ds_write_b16 v8, v1
	ds_write_b16_d16_hi v14, v1 offset:144
	s_waitcnt lgkmcnt(6)
	ds_write_b16 v8, v2 offset:288
	ds_write_b16_d16_hi v14, v2 offset:432
	ds_write_b16 v8, v3 offset:576
	ds_write_b16_d16_hi v14, v3 offset:720
	s_waitcnt lgkmcnt(9)
	ds_write_b16 v8, v10 offset:864
	ds_write_b16_d16_hi v14, v10 offset:1008
	ds_write_b16 v8, v11 offset:1152
	ds_write_b16_d16_hi v14, v11 offset:1296
	s_waitcnt lgkmcnt(12)
	ds_write_b16 v8, v12 offset:1440
	v_and_b32_e32 v0, 0x7f, v43
	v_lshlrev_b32_e32 v1, 6, v43
	v_lshlrev_b32_e32 v0, 2, v0
	v_and_b32_e32 v1, 0xffffe000, v1
	v_add3_u32 v10, 0, v0, v1
	ds_read2st64_b32 v[0:1], v10 offset1:2
	ds_write_b16_d16_hi v14, v12 offset:1584
	ds_write_b16 v8, v13 offset:1728
	ds_write_b16_d16_hi v14, v13 offset:1872
	ds_read2st64_b32 v[2:3], v10 offset0:4 offset1:6
	v_mul_f32_e32 v12, 0xbfb8aa3b, v56
	v_ashrrev_i32_e32 v22, 7, v43
	s_waitcnt lgkmcnt(4)
	v_add_f32_e32 v0, 0, v0
	v_add_f32_e32 v8, v0, v1
	ds_write2st64_b32 v10, v0, v8 offset1:2
	ds_read2st64_b32 v[0:1], v10 offset0:8 offset1:10
	s_waitcnt lgkmcnt(2)
	v_add_f32_e32 v2, v8, v2
	v_add_f32_e32 v8, v2, v3
	ds_write2st64_b32 v10, v2, v8 offset0:4 offset1:6
	ds_read2st64_b32 v[2:3], v10 offset0:12 offset1:14
	s_waitcnt lgkmcnt(2)
	v_add_f32_e32 v0, v8, v0
	v_add_f32_e32 v8, v0, v1
	ds_write2st64_b32 v10, v0, v8 offset0:8 offset1:10
	ds_read2st64_b32 v[0:1], v10 offset0:16 offset1:18
	s_waitcnt lgkmcnt(2)
	v_add_f32_e32 v2, v8, v2
	v_add_f32_e32 v8, v2, v3
	ds_write2st64_b32 v10, v2, v8 offset0:12 offset1:14
	ds_read2st64_b32 v[2:3], v10 offset0:20 offset1:22
	s_waitcnt lgkmcnt(2)
	v_add_f32_e32 v0, v8, v0
	v_add_f32_e32 v8, v0, v1
	ds_write2st64_b32 v10, v0, v8 offset0:16 offset1:18
	ds_read2st64_b32 v[0:1], v10 offset0:24 offset1:26
	s_waitcnt lgkmcnt(2)
	v_add_f32_e32 v8, v8, v2
	v_add_f32_e32 v11, v8, v3
	ds_read2st64_b32 v[2:3], v10 offset0:28 offset1:30
	ds_write2st64_b32 v10, v8, v11 offset0:20 offset1:22
	s_waitcnt lgkmcnt(2)
	v_add_f32_e32 v0, v11, v0
	v_add_f32_e32 v1, v0, v1
	ds_write2st64_b32 v10, v0, v1 offset0:24 offset1:26
	s_waitcnt lgkmcnt(2)
	v_add_f32_e32 v0, v1, v2
	v_add_f32_e32 v1, v0, v3
	ds_write2st64_b32 v10, v0, v1 offset0:28 offset1:30
	v_lshl_add_u32 v0, v43, 2, 0
	ds_write_b32 v0, v1 offset:32768
	s_waitcnt lgkmcnt(0)
	s_barrier
	ds_read2st64_b64 v[0:3], v58 offset0:64 offset1:65
	ds_read_b64 v[10:11], v58 offset:33792
	v_sub_u32_e32 v8, v58, v59
	v_exp_f32_e32 v58, v12
	v_mul_f32_e32 v12, 0xbfb8aa3b, v57
	v_exp_f32_e32 v59, v12
	ds_read_b64 v[12:13], v99
	s_waitcnt lgkmcnt(2)
	v_pk_add_f32 v[14:15], v[0:1], v[2:3]
	v_add_f32_e32 v58, 1.0, v58
	v_add_f32_e32 v59, 1.0, v59
	s_waitcnt lgkmcnt(1)
	v_pk_add_f32 v[10:11], v[14:15], v[10:11]
	v_cmp_eq_u32_e32 vcc, 2, v22
	v_rcp_f32_e32 v58, v58
	v_rcp_f32_e32 v59, v59
	v_cndmask_b32_e32 v2, v10, v14, vcc
	v_cmp_eq_u32_e64 s[8:9], 1, v22
	v_cmp_gt_u32_e64 s[10:11], s83, v43
	s_waitcnt lgkmcnt(0)
	v_exp_f32_e32 v72, v12
	v_cndmask_b32_e64 v2, v2, v0, s[8:9]
	v_exp_f32_e32 v73, v13
	v_cndmask_b32_e64 v3, v2, 0, s[10:11]
	v_cndmask_b32_e32 v2, v11, v15, vcc
	v_cndmask_b32_e64 v2, v2, v1, s[8:9]
	v_pk_mul_f32 v[56:57], v[58:59], v[56:57]
	s_mov_b32 s0, 0x3db504f3
	v_cndmask_b32_e64 v53, v2, 0, s[10:11]
	v_pk_mul_f32 v[56:57], v[56:57], s[0:1] op_sel_hi:[1,0]
	v_lshlrev_b32_e32 v2, 8, v45
	v_pk_mul_f32 v[58:59], v[56:57], v[72:73]
	v_add_f32_e32 v72, v12, v3
	v_add_f32_e32 v73, v13, v53
	v_exp_f32_e32 v72, v72
	v_exp_f32_e32 v73, v73
	v_sub_u32_e32 v2, v100, v2
	v_cvt_pk_bf16_f32 v99, v58, v59
	v_mad_u64_u32 v[58:59], s[6:7], v40, s52, v[8:9]
	v_pk_mul_f32 v[56:57], v[56:57], v[72:73]
	v_cmp_gt_i32_e32 vcc, 1, v22
	v_cvt_pk_bf16_f32 v56, v56, v57
	ds_write2st64_b32 v58, v99, v56 offset0:136 offset1:204
	s_and_saveexec_b64 s[6:7], vcc
	s_cbranch_execz .LBB0_1142
	v_sub_f32_e64 v56, -v3, v12
	v_sub_f32_e64 v57, -v53, v13
	v_min_f32_e32 v56, 0x42c80000, v56
	v_min_f32_e32 v57, 0x42c80000, v57
	v_exp_f32_e32 v56, v56
	v_exp_f32_e32 v57, v57
	s_nop 0
	v_pk_mul_f32 v[56:57], v[6:7], v[56:57]
	s_nop 0
	v_cvt_pk_bf16_f32 v58, v56, v57
	v_mad_u64_u32 v[56:57], s[8:9], v40, s52, v[2:3]
	ds_write_b32 v56, v58
